# xattn tiles 2+3 QK: LDS read->wait->MFMA ladder de-serialised (8 reads in flight, fresh VGPR buffers v104-151)
# baseline (speedup 1.0000x reference)
;     ...
;         for (int ks = 0; ks < DQK / 32; ++ks)
; #pragma unroll
;             for (int ni = 0; ni < 4; ++ni) { const bf16x8 kf = *(const bf16x8*)(cK + (ni * 16 + fr) * LDK + ks * 32 + fq * 8);
; #pragma unroll
;                 for (int mi = 0; mi < MIA; ++mi) s[mi][ni] = __builtin_amdgcn_mfma_f32_16x16x32_bf16(kf, qf[mi][ks], s[mi][ni], 0, 0, 0); }
;         }
;         __syncthreads();
;         slot = nslot;
;         if (live) {
;         bf16x8 pf[MIA][2];
; #pragma unroll
;         for (int mi = 0; mi < MIA; ++mi) {
;             float mx = -1e30f;
;             if (CAUSAL && kt * 64 + 63 > q0 + w * 16 * MIA) {
;                 const int qabs = q0 + w * 16 * MIA + mi * 16 + fr;
; #pragma unroll
;                 for (int ni = 0; ni < 4; ++ni)
; #pragma unroll
;                     for (int r = 0; r < 4; ++r) { const int kabs = kt * 64 + ni * 16 + fq * 4 + r; if (kabs > qabs) s[mi][ni][r] = -1e30f; }
;             }
; #pragma unroll
;             for (int ni = 0; ni < 4; ++ni) mx = fmaxf(mx, fmaxf(fmaxf(s[mi][ni][0], s[mi][ni][1]), fmaxf(s[mi][ni][2], s[mi][ni][3])));
;             mx = fmaxf(mx, __shfl_xor(mx, 16)); mx = fmaxf(mx, __shfl_xor(mx, 32));
;             const float mnew = fmaxf(mrun[mi], mx);
;             const float mc = mnew * scale_log2;
;             float ps = 0.f;
; #pragma unroll
;             for (int ni = 0; ni < 4; ++ni)
; #pragma unroll
;                 for (int r = 0; r < 4; ++r) { const float pv = __builtin_amdgcn_exp2f(__builtin_fmaf(s[mi][ni][r], scale_log2, -mc)); s[mi][ni][r] = pv; ps += pv; }
;             if (__builtin_amdgcn_ballot_w64(mnew > mrun[mi]) != 0ull) {
;                 const float alpha = __builtin_amdgcn_exp2f((mrun[mi] - mnew) * scale_log2);
;                 lrun[mi] *= alpha;
; #pragma unroll
;                 for (int di = 0; di < DV / 16; ++di) o[mi][di] *= alpha;
;             }
;             mrun[mi] = mnew;
;             lrun[mi] += ps;
.LBB0_381:
	s_or_b64 exec, exec, s[0:1]
	v_add_f32_e32 v25, 0, v101
	v_add_f32_e32 v25, v102, v25
	v_add_f32_e32 v25, v103, v25
	v_add_f32_e32 v25, v104, v25
	v_add_f32_e32 v25, v105, v25
	v_add_f32_e32 v25, v106, v25
	v_add_f32_e32 v25, v107, v25
	v_add_f32_e32 v25, v108, v25
	v_add_f32_e32 v25, v109, v25
	v_add_f32_e32 v25, v110, v25
	v_add_f32_e32 v25, v111, v25
	v_add_f32_e32 v25, v112, v25
	v_add_f32_e32 v25, v113, v25
	v_add_f32_e32 v25, v114, v25
	v_add_f32_e32 v25, v115, v25
	v_add_f32_e32 v25, v116, v25
	v_add_f32_e32 v99, v24, v25
	global_load_dwordx4 v[24:27], v[68:69], off offset:384
	global_load_dwordx4 v[28:31], v[70:71], off offset:384
	ds_read_b128 v[104:107], v90 offset:36864
	ds_read_b128 v[108:111], v90 offset:41472
	ds_read_b128 v[112:115], v90 offset:46080
	ds_read_b128 v[116:119], v90 offset:50688
	ds_read_b128 v[120:123], v90 offset:36928
	ds_read_b128 v[124:127], v90 offset:41536
	ds_read_b128 v[128:131], v90 offset:46144
	ds_read_b128 v[132:135], v90 offset:50752
	s_waitcnt lgkmcnt(7)
	v_mfma_f32_16x16x32_bf16 v[64:67], v[104:107], v[12:15], 0
	ds_read_b128 v[136:139], v90 offset:36992
	s_waitcnt lgkmcnt(7)
	v_mfma_f32_16x16x32_bf16 v[68:71], v[108:111], v[12:15], 0
	ds_read_b128 v[140:143], v90 offset:41600
	s_waitcnt lgkmcnt(7)
	v_mfma_f32_16x16x32_bf16 v[72:75], v[112:115], v[12:15], 0
	ds_read_b128 v[144:147], v90 offset:46208
	s_waitcnt lgkmcnt(7)
	v_mfma_f32_16x16x32_bf16 v[76:79], v[116:119], v[12:15], 0
	ds_read_b128 v[148:151], v90 offset:50816
	s_waitcnt lgkmcnt(7)
	v_mfma_f32_16x16x32_bf16 v[64:67], v[120:123], v[8:11], v[64:67]
	ds_read_b128 v[104:107], v90 offset:37056
	s_waitcnt lgkmcnt(7)
	v_mfma_f32_16x16x32_bf16 v[68:71], v[124:127], v[8:11], v[68:71]
	ds_read_b128 v[108:111], v90 offset:41664
	s_waitcnt lgkmcnt(7)
	v_mfma_f32_16x16x32_bf16 v[72:75], v[128:131], v[8:11], v[72:75]
	ds_read_b128 v[112:115], v90 offset:46272
	s_waitcnt lgkmcnt(7)
	v_mfma_f32_16x16x32_bf16 v[76:79], v[132:135], v[8:11], v[76:79]
	ds_read_b128 v[116:119], v90 offset:50880
	s_waitcnt lgkmcnt(7)
	v_mfma_f32_16x16x32_bf16 v[64:67], v[136:139], v[4:7], v[64:67]
	s_waitcnt lgkmcnt(6)
	v_mfma_f32_16x16x32_bf16 v[68:71], v[140:143], v[4:7], v[68:71]
	s_waitcnt lgkmcnt(5)
	v_mfma_f32_16x16x32_bf16 v[72:75], v[144:147], v[4:7], v[72:75]
	s_waitcnt lgkmcnt(4)
	v_mfma_f32_16x16x32_bf16 v[76:79], v[148:151], v[4:7], v[76:79]
	s_waitcnt lgkmcnt(3)
	v_mfma_f32_16x16x32_bf16 v[64:67], v[104:107], v[0:3], v[64:67]
	s_waitcnt lgkmcnt(2)
	v_mfma_f32_16x16x32_bf16 v[68:71], v[108:111], v[0:3], v[68:71]
	s_waitcnt lgkmcnt(1)
	v_mfma_f32_16x16x32_bf16 v[72:75], v[112:115], v[0:3], v[72:75]
	s_waitcnt lgkmcnt(0)
	v_mfma_f32_16x16x32_bf16 v[76:79], v[116:119], v[0:3], v[76:79]
	v_max_f32_e32 v93, v67, v67
	v_max_f32_e32 v101, v66, v66
	v_max_f32_e32 v93, v101, v93
	v_max_f32_e32 v101, v71, v71
	v_max3_f32 v93, v64, v65, v93
	v_max_f32_e32 v102, v70, v70
	v_max_f32_e32 v101, v102, v101
	v_max3_f32 v101, v68, v69, v101
	v_max3_f32 v93, v93, s17, v101
	v_max_f32_e32 v101, v75, v75
	v_max_f32_e32 v102, v74, v74
	v_max_f32_e32 v101, v102, v101
	s_nop 0
	v_max_f32_e32 v102, v79, v79
	v_max_f32_e32 v103, v78, v78
	v_max_f32_e32 v102, v103, v102
	v_max3_f32 v101, v72, v73, v101
	v_max3_f32 v102, v76, v77, v102
	v_max3_f32 v93, v93, v101, v102
	ds_bpermute_b32 v101, v82, v93
	s_waitcnt lgkmcnt(0)
	s_barrier
	v_max_f32_e32 v101, v101, v101
	v_max_f32_e32 v93, v93, v101
	ds_bpermute_b32 v101, v83, v93
	s_waitcnt lgkmcnt(0)
	v_max3_f32 v101, v92, v93, v101
	v_cmp_gt_f32_e32 vcc, v101, v92
	s_cbranch_vccz .LBB0_383
	v_sub_f32_e32 v92, v92, v101
	v_mul_f32_e32 v92, 0x3e0293ee, v92
	v_exp_f32_e32 v92, v92
	s_nop 0
	v_pk_mul_f32 v[38:39], v[38:39], v[92:93] op_sel_hi:[1,0]
	v_pk_mul_f32 v[36:37], v[36:37], v[92:93] op_sel_hi:[1,0]
	v_pk_mul_f32 v[50:51], v[50:51], v[92:93] op_sel_hi:[1,0]
	v_pk_mul_f32 v[48:49], v[48:49], v[92:93] op_sel_hi:[1,0]
	v_pk_mul_f32 v[54:55], v[54:55], v[92:93] op_sel_hi:[1,0]
	v_pk_mul_f32 v[52:53], v[52:53], v[92:93] op_sel_hi:[1,0]
	v_pk_mul_f32 v[58:59], v[58:59], v[92:93] op_sel_hi:[1,0]
	v_pk_mul_f32 v[56:57], v[56:57], v[92:93] op_sel_hi:[1,0]
	v_pk_mul_f32 v[62:63], v[62:63], v[92:93] op_sel_hi:[1,0]
	v_pk_mul_f32 v[60:61], v[60:61], v[92:93] op_sel_hi:[1,0]
	v_pk_mul_f32 v[46:47], v[46:47], v[92:93] op_sel_hi:[1,0]
	v_pk_mul_f32 v[44:45], v[44:45], v[92:93] op_sel_hi:[1,0]
	v_pk_mul_f32 v[42:43], v[42:43], v[92:93] op_sel_hi:[1,0]
	v_pk_mul_f32 v[40:41], v[40:41], v[92:93] op_sel_hi:[1,0]
	v_pk_mul_f32 v[34:35], v[34:35], v[92:93] op_sel_hi:[1,0]
	v_pk_mul_f32 v[32:33], v[32:33], v[92:93] op_sel_hi:[1,0]
	v_mul_f32_e32 v99, v99, v92

;     ...
;         for (int ks = 0; ks < DQK / 32; ++ks)
; #pragma unroll
;             for (int ni = 0; ni < 4; ++ni) { const bf16x8 kf = *(const bf16x8*)(cK + (ni * 16 + fr) * LDK + ks * 32 + fq * 8);
; #pragma unroll
;                 for (int mi = 0; mi < MIA; ++mi) s[mi][ni] = __builtin_amdgcn_mfma_f32_16x16x32_bf16(kf, qf[mi][ks], s[mi][ni], 0, 0, 0); }
;         }
;         __syncthreads();
;         slot = nslot;
;         if (live) {
;         bf16x8 pf[MIA][2];
; #pragma unroll
;         for (int mi = 0; mi < MIA; ++mi) {
;             float mx = -1e30f;
;             if (CAUSAL && kt * 64 + 63 > q0 + w * 16 * MIA) {
;                 const int qabs = q0 + w * 16 * MIA + mi * 16 + fr;
; #pragma unroll
;                 for (int ni = 0; ni < 4; ++ni)
; #pragma unroll
;                     for (int r = 0; r < 4; ++r) { const int kabs = kt * 64 + ni * 16 + fq * 4 + r; if (kabs > qabs) s[mi][ni][r] = -1e30f; }
;             }
; #pragma unroll
;             for (int ni = 0; ni < 4; ++ni) mx = fmaxf(mx, fmaxf(fmaxf(s[mi][ni][0], s[mi][ni][1]), fmaxf(s[mi][ni][2], s[mi][ni][3])));
;             mx = fmaxf(mx, __shfl_xor(mx, 16)); mx = fmaxf(mx, __shfl_xor(mx, 32));
;             const float mnew = fmaxf(mrun[mi], mx);
;             const float mc = mnew * scale_log2;
;             float ps = 0.f;
; #pragma unroll
;             for (int ni = 0; ni < 4; ++ni)
; #pragma unroll
;                 for (int r = 0; r < 4; ++r) { const float pv = __builtin_amdgcn_exp2f(__builtin_fmaf(s[mi][ni][r], scale_log2, -mc)); s[mi][ni][r] = pv; ps += pv; }
;             if (__builtin_amdgcn_ballot_w64(mnew > mrun[mi]) != 0ull) {
;                 const float alpha = __builtin_amdgcn_exp2f((mrun[mi] - mnew) * scale_log2);
;                 lrun[mi] *= alpha;
; #pragma unroll
;                 for (int di = 0; di < DV / 16; ++di) o[mi][di] *= alpha;
;             }
;             mrun[mi] = mnew;
;             lrun[mi] += ps;
.LBB0_387:
	s_or_b64 exec, exec, s[0:1]
	s_waitcnt vmcnt(2)
	v_add_f32_e32 v16, 0, v102
	v_add_f32_e32 v16, v103, v16
	v_add_f32_e32 v16, v104, v16
	v_add_f32_e32 v16, v105, v16
	v_add_f32_e32 v16, v106, v16
	v_add_f32_e32 v16, v107, v16
	v_add_f32_e32 v16, v108, v16
	v_add_f32_e32 v16, v109, v16
	v_add_f32_e32 v16, v72, v16
	v_add_f32_e32 v16, v73, v16
	v_add_f32_e32 v16, v74, v16
	v_add_f32_e32 v16, v75, v16
	v_add_f32_e32 v16, v76, v16
	v_add_f32_e32 v16, v77, v16
	v_add_f32_e32 v16, v78, v16
	v_add_f32_e32 v16, v79, v16
	s_waitcnt vmcnt(1)
	ds_write_b128 v95, v[24:27] offset:18432
	s_waitcnt vmcnt(0)
	ds_write_b128 v96, v[28:31] offset:18432
	v_add_u32_e32 v69, 0x12000, v90
	v_add_f32_e32 v68, v16, v99
	ds_read_b128 v[104:107], v69
	ds_read_b128 v[108:111], v69 offset:4608
	ds_read_b128 v[112:115], v69 offset:9216
	ds_read_b128 v[116:119], v69 offset:13824
	ds_read_b128 v[120:123], v69 offset:64
	ds_read_b128 v[124:127], v69 offset:4672
	ds_read_b128 v[128:131], v69 offset:9280
	ds_read_b128 v[132:135], v69 offset:13888
	s_waitcnt lgkmcnt(7)
	v_mfma_f32_16x16x32_bf16 v[20:23], v[104:107], v[12:15], 0
	ds_read_b128 v[136:139], v69 offset:128
	s_waitcnt lgkmcnt(7)
	v_mfma_f32_16x16x32_bf16 v[28:31], v[108:111], v[12:15], 0
	ds_read_b128 v[140:143], v69 offset:4736
	s_waitcnt lgkmcnt(7)
	v_mfma_f32_16x16x32_bf16 v[24:27], v[112:115], v[12:15], 0
	ds_read_b128 v[144:147], v69 offset:9344
	s_waitcnt lgkmcnt(7)
	v_mfma_f32_16x16x32_bf16 v[16:19], v[116:119], v[12:15], 0
	ds_read_b128 v[148:151], v69 offset:13952
	s_waitcnt lgkmcnt(7)
	v_mfma_f32_16x16x32_bf16 v[20:23], v[120:123], v[8:11], v[20:23]
	ds_read_b128 v[104:107], v69 offset:192
	s_waitcnt lgkmcnt(7)
	v_mfma_f32_16x16x32_bf16 v[28:31], v[124:127], v[8:11], v[28:31]
	ds_read_b128 v[108:111], v69 offset:4800
	s_waitcnt lgkmcnt(7)
	v_mfma_f32_16x16x32_bf16 v[24:27], v[128:131], v[8:11], v[24:27]
	ds_read_b128 v[112:115], v69 offset:9408
	s_waitcnt lgkmcnt(7)
	v_mfma_f32_16x16x32_bf16 v[16:19], v[132:135], v[8:11], v[16:19]
	ds_read_b128 v[116:119], v69 offset:14016
	s_waitcnt lgkmcnt(7)
	v_mfma_f32_16x16x32_bf16 v[20:23], v[136:139], v[4:7], v[20:23]
	s_waitcnt lgkmcnt(6)
	v_mfma_f32_16x16x32_bf16 v[28:31], v[140:143], v[4:7], v[28:31]
	s_waitcnt lgkmcnt(5)
	v_mfma_f32_16x16x32_bf16 v[24:27], v[144:147], v[4:7], v[24:27]
	s_waitcnt lgkmcnt(4)
	v_mfma_f32_16x16x32_bf16 v[16:19], v[148:151], v[4:7], v[16:19]
	s_waitcnt lgkmcnt(3)
	v_mfma_f32_16x16x32_bf16 v[20:23], v[104:107], v[0:3], v[20:23]
	s_waitcnt lgkmcnt(2)
	v_mfma_f32_16x16x32_bf16 v[28:31], v[108:111], v[0:3], v[28:31]
	s_waitcnt lgkmcnt(1)
	v_mfma_f32_16x16x32_bf16 v[24:27], v[112:115], v[0:3], v[24:27]
	s_waitcnt lgkmcnt(0)
	v_mfma_f32_16x16x32_bf16 v[16:19], v[116:119], v[0:3], v[16:19]
	v_max_f32_e32 v64, v23, v23
	v_max_f32_e32 v65, v22, v22
	v_max_f32_e32 v64, v65, v64
	v_max_f32_e32 v65, v31, v31
	v_max_f32_e32 v66, v30, v30
	v_max_f32_e32 v65, v66, v65
	v_max3_f32 v64, v20, v21, v64
	v_max3_f32 v65, v28, v29, v65
	v_max3_f32 v64, v64, s17, v65
	v_max_f32_e32 v65, v27, v27
	v_max_f32_e32 v66, v26, v26
	v_max_f32_e32 v65, v66, v65
	v_max_f32_e32 v66, v19, v19
	v_max_f32_e32 v67, v18, v18
	v_max_f32_e32 v66, v67, v66
	v_max3_f32 v65, v24, v25, v65
	v_max3_f32 v66, v16, v17, v66
	v_max3_f32 v64, v64, v65, v66
	ds_bpermute_b32 v65, v82, v64
	s_waitcnt lgkmcnt(0)
	s_barrier
	v_max_f32_e32 v65, v65, v65
	v_max_f32_e32 v64, v64, v65
	ds_bpermute_b32 v65, v83, v64
	s_waitcnt lgkmcnt(0)
	v_max3_f32 v69, v101, v64, v65
	v_cmp_gt_f32_e32 vcc, v69, v101
	s_cbranch_vccz .LBB0_389
	v_sub_f32_e32 v64, v101, v69
	v_mul_f32_e32 v64, 0x3e0293ee, v64
	v_exp_f32_e32 v64, v64
	s_nop 0
	v_pk_mul_f32 v[38:39], v[38:39], v[64:65] op_sel_hi:[1,0]
	v_pk_mul_f32 v[36:37], v[36:37], v[64:65] op_sel_hi:[1,0]
	v_pk_mul_f32 v[50:51], v[50:51], v[64:65] op_sel_hi:[1,0]
	v_pk_mul_f32 v[48:49], v[48:49], v[64:65] op_sel_hi:[1,0]
	v_pk_mul_f32 v[54:55], v[54:55], v[64:65] op_sel_hi:[1,0]
	v_pk_mul_f32 v[52:53], v[52:53], v[64:65] op_sel_hi:[1,0]
	v_pk_mul_f32 v[58:59], v[58:59], v[64:65] op_sel_hi:[1,0]
	v_pk_mul_f32 v[56:57], v[56:57], v[64:65] op_sel_hi:[1,0]
	v_pk_mul_f32 v[62:63], v[62:63], v[64:65] op_sel_hi:[1,0]
	v_pk_mul_f32 v[60:61], v[60:61], v[64:65] op_sel_hi:[1,0]
	v_pk_mul_f32 v[46:47], v[46:47], v[64:65] op_sel_hi:[1,0]
	v_pk_mul_f32 v[44:45], v[44:45], v[64:65] op_sel_hi:[1,0]
	v_pk_mul_f32 v[42:43], v[42:43], v[64:65] op_sel_hi:[1,0]
	v_pk_mul_f32 v[40:41], v[40:41], v[64:65] op_sel_hi:[1,0]
	v_pk_mul_f32 v[34:35], v[34:35], v[64:65] op_sel_hi:[1,0]
	v_pk_mul_f32 v[32:33], v[32:33], v[64:65] op_sel_hi:[1,0]
	v_mul_f32_e32 v68, v68, v64
